# FFN gate/up K-loop: A-half-1 LDS-DMA stages moved from the two 12-read phases (ph1, ph5) into the read-free phases (ph8, ph4); prologue stages SA11 of K-tile 1, tail no longer re-stages
# speedup vs baseline: 1.0001x; 1.0001x over previous
; #define WAIT_V8(n) asm volatile("s_waitcnt vmcnt(" #n ")" ::: "memory")
; #define BAR8 __builtin_amdgcn_s_barrier()
;     ...
;     STAGE8(SB8(0, 0), Bt, K, bcol, 0); STAGE8(SA8(0, 0), A, lda, brow, 0);
;     STAGE8(SB8(0, 1), Bt, K, bcol + 128, 0); STAGE8(SA8(0, 1), A, lda, brow + 128, 0);
;   }
;   if (wr == 1) BAR8;
;   WAIT_V8(4); BAR8;
;   STAGE8(SB8(1, 0), Bt, K, bcol, 1); STAGE8(SA8(1, 0), A, lda, brow, 1); STAGE8(SB8(1, 1), Bt, K, bcol + 128, 1);
;   WAIT_V8(6); BAR8;
.LBB0_1258:
	s_or_b64 exec, exec, s[8:9]
	v_add_u32_e32 v0, v150, v0
	v_and_b32_e32 v0, 0xfffffc00, v0
	v_sub_u32_e32 v0, v150, v0
	v_lshrrev_b32_e32 v6, 4, v0
	v_add_u32_e32 v1, v3, v1
	v_bitop3_b32 v7, v6, v0, 32 bitop3:0x6c
	v_ashrrev_i32_e32 v0, 31, v0
	v_ashrrev_i32_e32 v1, 6, v1
	v_lshrrev_b32_e32 v0, 26, v0
	v_lshlrev_b32_e32 v6, 3, v1
	v_add_u32_e32 v0, v7, v0
	v_and_b32_e32 v6, -16, v6
	v_ashrrev_i32_e32 v0, 6, v0
	s_and_b32 s1, s12, 63
	s_and_b32 s8, s20, 0xffffff00
	v_add_u32_e32 v6, v0, v6
	v_mul_i32_i24_e32 v0, 64, v0
	s_lshl_b32 s12, s1, 19
	s_ashr_i32 s9, s8, 31
	s_ashr_i32 s1, s0, 31
	v_lshlrev_b32_e32 v1, 5, v1
	v_sub_u32_e32 v0, v7, v0
	v_mov_b32_e32 v13, 1
	s_lshl_b64 s[14:15], s[8:9], 11
	s_lshl_b64 s[8:9], s[0:1], 11
	v_and_b32_e32 v1, 32, v1
	v_ashrrev_i16_sdwa v0, v13, sext(v0) dst_sel:DWORD dst_unused:UNUSED_PAD src0_sel:DWORD src1_sel:BYTE_0
	s_add_u32 s8, s4, s8
	v_add_u32_sdwa v0, v1, sext(v0) dst_sel:DWORD dst_unused:UNUSED_PAD src0_sel:DWORD src1_sel:WORD_0
	v_ashrrev_i32_e32 v7, 31, v6
	v_readlane_b32 s40, v254, 35
	s_addc_u32 s9, s5, s9
	v_lshlrev_b64 v[132:133], 11, v[6:7]
	v_ashrrev_i32_e32 v1, 31, v0
	v_readlane_b32 s41, v254, 36
	v_lshl_add_u64 v[6:7], s[8:9], 0, v[132:133]
	v_lshlrev_b64 v[8:9], 1, v[0:1]
	v_add_u32_e32 v164, 0x18000, v150
	s_mov_b32 s13, s40
	v_lshl_add_u64 v[6:7], v[6:7], 0, v[8:9]
	s_mov_b64 s[40:41], 0x80
	v_readfirstlane_b32 s1, v164
	v_lshl_add_u64 v[6:7], v[6:7], 0, s[40:41]
	s_mov_b32 m0, s1
	s_waitcnt vmcnt(4)
	s_barrier
	global_load_lds_dwordx4 v[6:7], off
	v_ashrrev_i32_e32 v6, 31, v152
	v_lshrrev_b32_e32 v6, 22, v6
	v_add_u32_e32 v6, v152, v6
	v_ashrrev_i32_e32 v7, 10, v6
	v_mul_i32_i24_e32 v6, 0x400, v7
	v_sub_u32_e32 v6, v152, v6
	v_lshrrev_b32_e32 v10, 4, v6
	v_bitop3_b32 v10, v10, v6, 32 bitop3:0x6c
	v_ashrrev_i32_e32 v11, 31, v10
	v_lshrrev_b32_e32 v11, 26, v11
	v_add_u32_e32 v11, v10, v11
	v_lshlrev_b32_e32 v6, 3, v7
	v_ashrrev_i32_e32 v12, 6, v11
	v_and_b32_e32 v11, 0xc0, v11
	v_and_b32_e32 v6, -16, v6
	v_lshlrev_b32_e32 v7, 5, v7
	v_sub_u32_e32 v10, v10, v11
	v_add_u32_e32 v6, v12, v6
	v_and_b32_e32 v7, 32, v7
	v_ashrrev_i16_sdwa v10, v13, sext(v10) dst_sel:DWORD dst_unused:UNUSED_PAD src0_sel:DWORD src1_sel:BYTE_0
	v_add_u32_sdwa v134, v7, sext(v10) dst_sel:DWORD dst_unused:UNUSED_PAD src0_sel:DWORD src1_sel:WORD_0
	v_ashrrev_i32_e32 v7, 31, v6
	v_add_u32_e32 v165, 0x1a000, v150
	v_lshlrev_b64 v[136:137], 11, v[6:7]
	v_ashrrev_i32_e32 v135, 31, v134
	v_readfirstlane_b32 s1, v165
	v_lshl_add_u64 v[6:7], s[8:9], 0, v[136:137]
	v_lshlrev_b64 v[10:11], 1, v[134:135]
	s_mov_b32 m0, s1
	s_lshl_b32 s1, s27, 11
	v_lshl_add_u64 v[6:7], v[6:7], 0, v[10:11]
	s_waitcnt lgkmcnt(0)
	s_add_u32 s8, s2, s1
	v_lshl_add_u64 v[6:7], v[6:7], 0, s[40:41]
	s_addc_u32 s9, s3, 0
	global_load_lds_dwordx4 v[6:7], off
	v_lshl_add_u64 v[6:7], s[8:9], 0, v[132:133]
	v_add_u32_e32 v166, 0x8000, v150
	v_lshl_add_u64 v[6:7], v[6:7], 0, v[8:9]
	v_readfirstlane_b32 s1, v166
	s_or_b32 s36, s0, 0x80
	v_lshl_add_u64 v[6:7], v[6:7], 0, s[40:41]
	s_mov_b32 m0, s1
	s_ashr_i32 s37, s36, 31
	global_load_lds_dwordx4 v[6:7], off
	v_lshl_add_u64 v[6:7], s[8:9], 0, v[136:137]
	v_add_u32_e32 v167, 0xa000, v150
	s_lshl_b64 s[36:37], s[36:37], 11
	v_lshl_add_u64 v[6:7], v[6:7], 0, v[10:11]
	v_readfirstlane_b32 s1, v167
	s_add_u32 s36, s4, s36
	v_lshl_add_u64 v[6:7], v[6:7], 0, s[40:41]
	s_mov_b32 m0, s1
	s_addc_u32 s37, s5, s37
	global_load_lds_dwordx4 v[6:7], off
	v_lshl_add_u64 v[6:7], s[36:37], 0, v[132:133]
	v_add_u32_e32 v168, 0x1c000, v150
	v_lshl_add_u64 v[6:7], v[6:7], 0, v[8:9]
	v_readfirstlane_b32 s1, v168
	v_lshl_add_u64 v[6:7], v[6:7], 0, s[40:41]
	s_mov_b32 m0, s1
	v_add_u32_e32 v170, 0x1e000, v150
	global_load_lds_dwordx4 v[6:7], off
	v_lshl_add_u64 v[6:7], s[36:37], 0, v[136:137]
	v_lshl_add_u64 v[6:7], v[6:7], 0, v[10:11]
	v_readfirstlane_b32 s1, v170
	v_lshl_add_u64 v[6:7], v[6:7], 0, s[40:41]
	s_mov_b32 m0, s1
	v_and_b32_e32 v147, 15, v3
	global_load_lds_dwordx4 v[6:7], off
	v_bfe_u32 v148, v3, 4, 2
	v_lshlrev_b32_e32 v6, 4, v148
	v_lshlrev_b32_e32 v7, 6, v147
	v_lshlrev_b32_e32 v14, 2, v3
	v_or_b32_e32 v13, v6, v7
	v_and_b32_e32 v14, 32, v14
	s_mov_b32 s1, 0x10000
	v_bitop3_b32 v16, v13, s1, v14 bitop3:0xde
	s_mov_b32 s1, 0x14000
	v_bitop3_b32 v15, v6, v14, v7 bitop3:0x36
	v_bitop3_b32 v17, v13, s1, v14 bitop3:0xde
	s_mov_b32 s1, 0x18000
	v_lshlrev_b32_e32 v7, 6, v3
	v_bitop3_b32 v18, v13, s1, v14 bitop3:0xde
	s_mov_b32 s1, 0x1c000
	v_and_b32_e32 v7, 0x3c0, v7
	v_bitop3_b32 v13, v13, s1, v14 bitop3:0xde
	v_bitop3_b32 v14, v7, v14, v6 bitop3:0x36
	v_lshl_add_u64 v[6:7], s[12:13], 0, v[132:133]
	v_lshl_add_u64 v[6:7], v[6:7], 0, v[8:9]
	v_lshl_add_u64 v[138:139], s[2:3], 0, v[6:7]
	v_lshl_add_u64 v[6:7], s[12:13], 0, v[136:137]
	v_lshl_add_u64 v[6:7], v[6:7], 0, v[10:11]
	v_lshl_add_u64 v[140:141], s[2:3], 0, v[6:7]
	v_lshl_add_u64 v[6:7], s[14:15], 0, v[132:133]
	v_lshl_add_u64 v[6:7], v[6:7], 0, v[8:9]
	v_bfe_u32 v146, v3, 6, 2
	s_waitcnt vmcnt(6)
; #define LDA8(dst, b, h) _Pragma("unroll") for (int m = 0; m < 4; ++m) _Pragma("unroll") for (int k = 0; k < 2; ++k) \
;     dst[m][k] = *(const bf16x8*)((const char*)SA8(b, h) + lds_byte8(wr * 64 + m * 16 + fr, k * 32 + fq * 8))
; #define LDB8(dst, b, h) _Pragma("unroll") for (int n = 0; n < 2; ++n) _Pragma("unroll") for (int k = 0; k < 2; ++k) \
;     dst[n][k] = *(const bf16x8*)((const char*)SB8(b, h) + lds_byte8(wc * 32 + n * 16 + fr, k * 32 + fq * 8))
; #define WAIT_V8(n) asm volatile("s_waitcnt vmcnt(" #n ")" ::: "memory")
; #define WAIT_L8(n) asm volatile("s_waitcnt lgkmcnt(" #n ")" ::: "memory")
; #define BAR8 __builtin_amdgcn_s_barrier()
; #define SCHED8 __builtin_amdgcn_sched_barrier(0)
;     ...
;   {
;     float zinit = 0.f;
;     asm volatile("" : "+v"(zinit));
; #pragma unroll
;     for (int a = 0; a < 2; ++a)
; #pragma unroll
;       for (int b = 0; b < 2; ++b)
; #pragma unroll
;         for (int m = 0; m < 4; ++m)
; #pragma unroll
;           for (int n = 0; n < 2; ++n)
; #pragma unroll
;             for (int j = 0; j < 4; ++j) acc[a][b][m][n][j] = zinit;
;   }
;   bf16x8 At[4][2], B0[2][2], B1[2][2];
;   const int nt = K / 64;
;   if (!pre) {
;     STAGE8(SB8(0, 0), Bt, K, bcol, 0); STAGE8(SA8(0, 0), A, lda, brow, 0);
;     STAGE8(SB8(0, 1), Bt, K, bcol + 128, 0); STAGE8(SA8(0, 1), A, lda, brow + 128, 0);
;   }
;   if (wr == 1) BAR8;
;   WAIT_V8(4); BAR8;
;   STAGE8(SB8(1, 0), Bt, K, bcol, 1); STAGE8(SA8(1, 0), A, lda, brow, 1); STAGE8(SB8(1, 1), Bt, K, bcol + 128, 1);
;   WAIT_V8(6); BAR8;
;   for (int tt = 0; tt < nt - 2; tt += 2) {
;     LDB8(B0, 0, 0); SCHED8; LDA8(At, 0, 0); STAGE8(SA8(1, 1), A, lda, brow + 128, tt + 1);
;     WAIT_L8(8); BAR8; WAIT_L8(0); MMA8(0, 0, At, B0); BAR8; SCHED8;
	v_lshlrev_b32_e32 v149, 6, v5
	v_lshlrev_b32_e32 v5, 13, v5
	v_lshl_add_u64 v[142:143], s[6:7], 0, v[6:7]
	v_lshl_add_u64 v[6:7], s[14:15], 0, v[136:137]
	v_readlane_b32 s42, v254, 37
	v_readlane_b32 s43, v254, 38
	v_lshlrev_b32_e32 v12, 12, v146
	v_or_b32_e32 v19, 0x800, v5
	v_or_b32_e32 v20, 0x1000, v5
	v_or_b32_e32 v21, 0x1800, v5
	v_lshl_add_u64 v[6:7], v[6:7], 0, v[10:11]
	v_lshl_add_u64 v[144:145], s[6:7], 0, v[6:7]
	s_mov_b32 s1, -2
	s_mov_b64 s[12:13], 0
	v_add_u32_e32 v171, v16, v12
	v_add_u32_e32 v161, v15, v5
	v_add_u32_e32 v160, v14, v19
	v_add_u32_e32 v159, v14, v20
	v_add_u32_e32 v158, v14, v21
	v_add_u32_e32 v169, v17, v12
	v_add_u32_e32 v163, v18, v12
	v_add_u32_e32 v162, v13, v12
	v_mov_b32_e32 v5, v4
	v_mov_b32_e32 v6, v4
	v_mov_b32_e32 v7, v4
	v_mov_b32_e32 v8, v4
	v_mov_b32_e32 v9, v4
	v_mov_b32_e32 v10, v4
	v_mov_b32_e32 v11, v4
	v_mov_b32_e32 v12, v4
	v_mov_b32_e32 v13, v4
	v_mov_b32_e32 v14, v4
	v_mov_b32_e32 v15, v4
	v_mov_b32_e32 v16, v4
	v_mov_b32_e32 v17, v4
	v_mov_b32_e32 v18, v4
	v_mov_b32_e32 v19, v4
	v_mov_b32_e32 v20, v4
	v_mov_b32_e32 v21, v4
	v_mov_b32_e32 v22, v4
	v_mov_b32_e32 v23, v4
	v_mov_b32_e32 v24, v4
	v_mov_b32_e32 v25, v4
	v_mov_b32_e32 v26, v4
	v_mov_b32_e32 v27, v4
	v_mov_b32_e32 v28, v4
	v_mov_b32_e32 v29, v4
	v_mov_b32_e32 v30, v4
	v_mov_b32_e32 v31, v4
	v_mov_b32_e32 v32, v4
	v_mov_b32_e32 v33, v4
	v_mov_b32_e32 v34, v4
	v_mov_b32_e32 v35, v4
	v_mov_b32_e32 v36, v4
	v_mov_b32_e32 v37, v4
	v_mov_b32_e32 v38, v4
	v_mov_b32_e32 v39, v4
	v_mov_b32_e32 v40, v4
	v_mov_b32_e32 v41, v4
	v_mov_b32_e32 v42, v4
	v_mov_b32_e32 v43, v4
	v_mov_b32_e32 v44, v4
	v_mov_b32_e32 v45, v4
	v_mov_b32_e32 v46, v4
	v_mov_b32_e32 v47, v4
	v_mov_b32_e32 v48, v4
	v_mov_b32_e32 v49, v4
	v_mov_b32_e32 v50, v4
	v_mov_b32_e32 v51, v4
	v_mov_b32_e32 v52, v4
	v_mov_b32_e32 v53, v4
	v_mov_b32_e32 v54, v4
	v_mov_b32_e32 v55, v4
	v_mov_b32_e32 v56, v4
	v_mov_b32_e32 v57, v4
	v_mov_b32_e32 v58, v4
	v_mov_b32_e32 v59, v4
	v_mov_b32_e32 v60, v4
	v_mov_b32_e32 v61, v4
	v_mov_b32_e32 v62, v4
	v_mov_b32_e32 v63, v4
	v_mov_b32_e32 v64, v4
	v_mov_b32_e32 v65, v4
	v_mov_b32_e32 v66, v4
	v_mov_b32_e32 v67, v4
	v_mov_b32_e32 v68, v4
	v_mov_b32_e32 v69, v4
	v_mov_b32_e32 v70, v4
	v_mov_b32_e32 v71, v4
	v_mov_b32_e32 v72, v4
	v_mov_b32_e32 v73, v4
	v_mov_b32_e32 v74, v4
	v_mov_b32_e32 v75, v4
	v_mov_b32_e32 v76, v4
	v_mov_b32_e32 v77, v4
	v_mov_b32_e32 v78, v4
	v_mov_b32_e32 v79, v4
	v_mov_b32_e32 v80, v4
	v_mov_b32_e32 v81, v4
	v_mov_b32_e32 v82, v4
	v_mov_b32_e32 v83, v4
	v_mov_b32_e32 v84, v4
	v_mov_b32_e32 v85, v4
	v_mov_b32_e32 v86, v4
	v_mov_b32_e32 v87, v4
	v_mov_b32_e32 v88, v4
	v_mov_b32_e32 v89, v4
	v_mov_b32_e32 v90, v4
	v_mov_b32_e32 v91, v4
	v_mov_b32_e32 v92, v4
	v_mov_b32_e32 v93, v4
	v_mov_b32_e32 v94, v4
	v_mov_b32_e32 v95, v4
	v_mov_b32_e32 v96, v4
	v_mov_b32_e32 v97, v4
	v_mov_b32_e32 v98, v4
	v_mov_b32_e32 v99, v4
	v_mov_b32_e32 v100, v4
	v_mov_b32_e32 v101, v4
	v_mov_b32_e32 v102, v4
	v_mov_b32_e32 v103, v4
	v_mov_b32_e32 v104, v4
	v_mov_b32_e32 v105, v4
	v_mov_b32_e32 v106, v4
	v_mov_b32_e32 v107, v4
	v_mov_b32_e32 v108, v4
	v_mov_b32_e32 v109, v4
	v_mov_b32_e32 v110, v4
	v_mov_b32_e32 v111, v4
	v_mov_b32_e32 v112, v4
	v_mov_b32_e32 v113, v4
	v_mov_b32_e32 v114, v4
	v_mov_b32_e32 v115, v4
	v_mov_b32_e32 v116, v4
	v_mov_b32_e32 v117, v4
	v_mov_b32_e32 v118, v4
	v_mov_b32_e32 v119, v4
	v_mov_b32_e32 v120, v4
	v_mov_b32_e32 v121, v4
	v_mov_b32_e32 v122, v4
	v_mov_b32_e32 v123, v4
	v_mov_b32_e32 v124, v4
	v_mov_b32_e32 v125, v4
	v_mov_b32_e32 v126, v4
	v_mov_b32_e32 v127, v4
	v_mov_b32_e32 v128, v4
	v_mov_b32_e32 v129, v4
	v_mov_b32_e32 v130, v4
	v_mov_b32_e32 v131, v4
	s_mov_b64 s[36:37], 0xcaa0100
	s_mov_b64 s[40:41], 0xcae0100
	s_mov_b64 s[42:43], 0xcaa0180
	s_mov_b64 s[44:45], 0xcae0180
	s_mov_b64 s[100:101], 0x40180
	v_add_u32_e32 v174, 0xc000, v150
	v_add_u32_e32 v175, 0xe000, v150
	v_lshl_add_u64 v[222:223], v[138:139], 0, s[34:35]
	v_readfirstlane_b32 s14, v174
	s_mov_b32 m0, s14
	v_readfirstlane_b32 s14, v175
	global_load_lds_dwordx4 v[222:223], off
	v_lshl_add_u64 v[222:223], v[140:141], 0, s[34:35]
	s_mov_b32 m0, s14
	s_nop 0
	global_load_lds_dwordx4 v[222:223], off
	s_barrier
.LBB0_1259:
	ds_read_b128 v[174:177], v171
	ds_read_b128 v[178:181], v171 offset:1024
	ds_read_b128 v[182:185], v171 offset:2048
	ds_read_b128 v[186:189], v171 offset:3072
	v_lshl_add_u64 v[222:223], v[138:139], 0, s[12:13]
	v_lshl_add_u64 v[236:237], v[140:141], 0, s[12:13]
	ds_read_b128 v[190:193], v161
	ds_read_b128 v[194:197], v161 offset:1024
	ds_read_b128 v[198:201], v160
	ds_read_b128 v[202:205], v160 offset:1024
	ds_read_b128 v[206:209], v159
	ds_read_b128 v[210:213], v159 offset:1024
	ds_read_b128 v[214:217], v158
	ds_read_b128 v[218:221], v158 offset:1024
	s_waitcnt lgkmcnt(8)
	s_barrier
	s_waitcnt lgkmcnt(0)
	s_setprio 1
	s_waitcnt lgkmcnt(0)
	v_mfma_f32_16x16x32_f16 v[128:131], v[190:193], v[174:177], v[128:131]
	v_mfma_f32_16x16x32_f16 v[124:127], v[190:193], v[182:185], v[124:127]
	v_mfma_f32_16x16x32_f16 v[120:123], v[198:201], v[174:177], v[120:123]
	v_mfma_f32_16x16x32_f16 v[116:119], v[198:201], v[182:185], v[116:119]
	v_mfma_f32_16x16x32_f16 v[112:115], v[206:209], v[174:177], v[112:115]
	v_mfma_f32_16x16x32_f16 v[108:111], v[206:209], v[182:185], v[108:111]
	v_mfma_f32_16x16x32_f16 v[104:107], v[214:217], v[174:177], v[104:107]
	v_mfma_f32_16x16x32_f16 v[100:103], v[214:217], v[182:185], v[100:103]
	v_mfma_f32_16x16x32_f16 v[128:131], v[194:197], v[178:181], v[128:131]
	v_mfma_f32_16x16x32_f16 v[124:127], v[194:197], v[186:189], v[124:127]
	v_mfma_f32_16x16x32_f16 v[120:123], v[202:205], v[178:181], v[120:123]
	v_mfma_f32_16x16x32_f16 v[116:119], v[202:205], v[186:189], v[116:119]
	v_mfma_f32_16x16x32_f16 v[112:115], v[210:213], v[178:181], v[112:115]
	v_mfma_f32_16x16x32_f16 v[108:111], v[210:213], v[186:189], v[108:111]
	v_mfma_f32_16x16x32_f16 v[104:107], v[218:221], v[178:181], v[104:107]
	v_mfma_f32_16x16x32_f16 v[100:103], v[218:221], v[186:189], v[100:103]
	s_setprio 0
	s_barrier
; #define LDA8(dst, b, h) _Pragma("unroll") for (int m = 0; m < 4; ++m) _Pragma("unroll") for (int k = 0; k < 2; ++k) \
;     dst[m][k] = *(const bf16x8*)((const char*)SA8(b, h) + lds_byte8(wr * 64 + m * 16 + fr, k * 32 + fq * 8))
; #define LDB8(dst, b, h) _Pragma("unroll") for (int n = 0; n < 2; ++n) _Pragma("unroll") for (int k = 0; k < 2; ++k) \
;     dst[n][k] = *(const bf16x8*)((const char*)SB8(b, h) + lds_byte8(wc * 32 + n * 16 + fr, k * 32 + fq * 8))
; #define WAIT_V8(n) asm volatile("s_waitcnt vmcnt(" #n ")" ::: "memory")
; #define WAIT_L8(n) asm volatile("s_waitcnt lgkmcnt(" #n ")" ::: "memory")
; #define BAR8 __builtin_amdgcn_s_barrier()
; #define SCHED8 __builtin_amdgcn_sched_barrier(0)
;     ...
;     WAIT_L8(8); BAR8; WAIT_L8(0); MMA8(0, 0, At, B0); BAR8; SCHED8;
;     LDB8(B1, 0, 1); STAGE8(SB8(0, 0), Bt, K, bcol, tt + 2);
;     BAR8; WAIT_L8(0); MMA8(0, 1, At, B1); BAR8;
;     LDA8(At, 0, 1); STAGE8(SA8(0, 0), A, lda, brow, tt + 2);
;     BAR8; WAIT_L8(0); MMA8(1, 0, At, B0); BAR8; SCHED8;
;     STAGE8(SB8(0, 1), Bt, K, bcol + 128, tt + 2);
;     WAIT_V8(6); BAR8; MMA8(1, 1, At, B1); BAR8;
	v_lshl_add_u64 v[246:247], v[142:143], 0, s[12:13]
	v_readfirstlane_b32 s14, v151
	v_lshl_add_u64 v[248:249], v[246:247], 0, s[36:37]
	s_mov_b32 m0, s14
	ds_read_b128 v[226:229], v169
	ds_read_b128 v[230:233], v169 offset:1024
	ds_read_b128 v[238:241], v169 offset:2048
	ds_read_b128 v[242:245], v169 offset:3072
	global_load_lds_dwordx4 v[248:249], off
	v_lshl_add_u64 v[248:249], v[144:145], 0, s[12:13]
	v_readfirstlane_b32 s14, v153
	v_lshl_add_u64 v[250:251], v[248:249], 0, s[36:37]
	s_mov_b32 m0, s14
	s_nop 0
	global_load_lds_dwordx4 v[250:251], off
	s_barrier
	s_waitcnt lgkmcnt(0)
	s_setprio 1
	s_waitcnt lgkmcnt(0)
	v_mfma_f32_16x16x32_f16 v[96:99], v[190:193], v[226:229], v[96:99]
	v_mfma_f32_16x16x32_f16 v[92:95], v[190:193], v[238:241], v[92:95]
	v_mfma_f32_16x16x32_f16 v[88:91], v[198:201], v[226:229], v[88:91]
	v_mfma_f32_16x16x32_f16 v[84:87], v[198:201], v[238:241], v[84:87]
	v_mfma_f32_16x16x32_f16 v[80:83], v[206:209], v[226:229], v[80:83]
	v_mfma_f32_16x16x32_f16 v[76:79], v[206:209], v[238:241], v[76:79]
	v_mfma_f32_16x16x32_f16 v[72:75], v[214:217], v[226:229], v[72:75]
	v_mfma_f32_16x16x32_f16 v[68:71], v[214:217], v[238:241], v[68:71]
	v_mfma_f32_16x16x32_f16 v[96:99], v[194:197], v[230:233], v[96:99]
	v_mfma_f32_16x16x32_f16 v[92:95], v[194:197], v[242:245], v[92:95]
	v_mfma_f32_16x16x32_f16 v[88:91], v[202:205], v[230:233], v[88:91]
	v_mfma_f32_16x16x32_f16 v[84:87], v[202:205], v[242:245], v[84:87]
	v_mfma_f32_16x16x32_f16 v[80:83], v[210:213], v[230:233], v[80:83]
	v_mfma_f32_16x16x32_f16 v[76:79], v[210:213], v[242:245], v[76:79]
	v_mfma_f32_16x16x32_f16 v[72:75], v[218:221], v[230:233], v[72:75]
	v_mfma_f32_16x16x32_f16 v[68:71], v[218:221], v[242:245], v[68:71]
	s_setprio 0
	v_readfirstlane_b32 s14, v150
	v_lshl_add_u64 v[250:251], v[222:223], 0, s[10:11]
	s_mov_b32 m0, s14
	v_readfirstlane_b32 s14, v152
	s_barrier
	ds_read_b128 v[190:193], v161 offset:16384
	ds_read_b128 v[194:197], v161 offset:17408
	ds_read_b128 v[198:201], v160 offset:16384
	ds_read_b128 v[202:205], v160 offset:17408
	ds_read_b128 v[206:209], v159 offset:16384
	ds_read_b128 v[210:213], v159 offset:17408
	ds_read_b128 v[214:217], v158 offset:16384
	ds_read_b128 v[218:221], v158 offset:17408
	global_load_lds_dwordx4 v[250:251], off
	v_lshl_add_u64 v[250:251], v[236:237], 0, s[10:11]
	s_mov_b32 m0, s14
	s_nop 0
	global_load_lds_dwordx4 v[250:251], off
	s_barrier
	s_waitcnt lgkmcnt(0)
	s_setprio 1
	s_waitcnt lgkmcnt(0)
	v_mfma_f32_16x16x32_f16 v[64:67], v[190:193], v[174:177], v[64:67]
	v_mfma_f32_16x16x32_f16 v[60:63], v[190:193], v[182:185], v[60:63]
	v_mfma_f32_16x16x32_f16 v[56:59], v[198:201], v[174:177], v[56:59]
	v_mfma_f32_16x16x32_f16 v[52:55], v[198:201], v[182:185], v[52:55]
	v_mfma_f32_16x16x32_f16 v[48:51], v[206:209], v[174:177], v[48:51]
	v_mfma_f32_16x16x32_f16 v[44:47], v[206:209], v[182:185], v[44:47]
	v_mfma_f32_16x16x32_f16 v[40:43], v[214:217], v[174:177], v[40:43]
	v_mfma_f32_16x16x32_f16 v[36:39], v[214:217], v[182:185], v[36:39]
	v_mfma_f32_16x16x32_f16 v[64:67], v[194:197], v[178:181], v[64:67]
	v_mfma_f32_16x16x32_f16 v[60:63], v[194:197], v[186:189], v[60:63]
	v_mfma_f32_16x16x32_f16 v[56:59], v[202:205], v[178:181], v[56:59]
	v_mfma_f32_16x16x32_f16 v[52:55], v[202:205], v[186:189], v[52:55]
	v_mfma_f32_16x16x32_f16 v[48:51], v[210:213], v[178:181], v[48:51]
	v_mfma_f32_16x16x32_f16 v[44:47], v[210:213], v[186:189], v[44:47]
	v_mfma_f32_16x16x32_f16 v[40:43], v[218:221], v[178:181], v[40:43]
	v_mfma_f32_16x16x32_f16 v[36:39], v[218:221], v[186:189], v[36:39]
	s_setprio 0
	s_barrier
	v_readfirstlane_b32 s14, v154
	v_lshl_add_u64 v[174:175], v[246:247], 0, s[40:41]
	s_mov_b32 m0, s14
	v_readfirstlane_b32 s14, v155
	global_load_lds_dwordx4 v[174:175], off
	v_lshl_add_u64 v[174:175], v[248:249], 0, s[40:41]
	s_mov_b32 m0, s14
	s_nop 0
	global_load_lds_dwordx4 v[174:175], off
	v_readfirstlane_b32 s14, v156
	v_lshl_add_u64 v[174:175], v[222:223], 0, s[18:19]
	s_mov_b32 m0, s14
	v_readfirstlane_b32 s14, v157
	global_load_lds_dwordx4 v[174:175], off
	v_lshl_add_u64 v[174:175], v[236:237], 0, s[18:19]
	s_mov_b32 m0, s14
	s_nop 0
	global_load_lds_dwordx4 v[174:175], off
	s_waitcnt vmcnt(8)
	s_barrier
	s_setprio 1
	v_mfma_f32_16x16x32_f16 v[32:35], v[190:193], v[226:229], v[32:35]
	v_mfma_f32_16x16x32_f16 v[28:31], v[190:193], v[238:241], v[28:31]
	v_mfma_f32_16x16x32_f16 v[24:27], v[198:201], v[226:229], v[24:27]
	v_mfma_f32_16x16x32_f16 v[20:23], v[198:201], v[238:241], v[20:23]
	v_mfma_f32_16x16x32_f16 v[16:19], v[206:209], v[226:229], v[16:19]
	v_mfma_f32_16x16x32_f16 v[12:15], v[206:209], v[238:241], v[12:15]
	v_mfma_f32_16x16x32_f16 v[8:11], v[214:217], v[226:229], v[8:11]
	v_mfma_f32_16x16x32_f16 v[4:7], v[214:217], v[238:241], v[4:7]
	v_mfma_f32_16x16x32_f16 v[32:35], v[194:197], v[230:233], v[32:35]
	v_mfma_f32_16x16x32_f16 v[28:31], v[194:197], v[242:245], v[28:31]
	v_mfma_f32_16x16x32_f16 v[24:27], v[202:205], v[230:233], v[24:27]
	v_mfma_f32_16x16x32_f16 v[20:23], v[202:205], v[242:245], v[20:23]
	v_mfma_f32_16x16x32_f16 v[16:19], v[210:213], v[230:233], v[16:19]
	v_mfma_f32_16x16x32_f16 v[12:15], v[210:213], v[242:245], v[12:15]
	v_mfma_f32_16x16x32_f16 v[8:11], v[218:221], v[230:233], v[8:11]
	v_mfma_f32_16x16x32_f16 v[4:7], v[218:221], v[242:245], v[4:7]
	s_setprio 0
	s_barrier
	ds_read_b128 v[174:177], v163
	ds_read_b128 v[178:181], v163 offset:1024
	ds_read_b128 v[182:185], v163 offset:2048
	ds_read_b128 v[186:189], v163 offset:3072
	ds_read_b128 v[190:193], v161 offset:32768
	ds_read_b128 v[194:197], v161 offset:33792
	ds_read_b128 v[198:201], v160 offset:32768
	ds_read_b128 v[202:205], v160 offset:33792
	ds_read_b128 v[206:209], v159 offset:32768
	ds_read_b128 v[210:213], v159 offset:33792
	ds_read_b128 v[214:217], v158 offset:32768
	ds_read_b128 v[218:221], v158 offset:33792
	s_waitcnt lgkmcnt(8)
	s_barrier
; #define LDA8(dst, b, h) _Pragma("unroll") for (int m = 0; m < 4; ++m) _Pragma("unroll") for (int k = 0; k < 2; ++k) \
;     dst[m][k] = *(const bf16x8*)((const char*)SA8(b, h) + lds_byte8(wr * 64 + m * 16 + fr, k * 32 + fq * 8))
; #define LDB8(dst, b, h) _Pragma("unroll") for (int n = 0; n < 2; ++n) _Pragma("unroll") for (int k = 0; k < 2; ++k) \
;     dst[n][k] = *(const bf16x8*)((const char*)SB8(b, h) + lds_byte8(wc * 32 + n * 16 + fr, k * 32 + fq * 8))
; #define WAIT_V8(n) asm volatile("s_waitcnt vmcnt(" #n ")" ::: "memory")
; #define WAIT_L8(n) asm volatile("s_waitcnt lgkmcnt(" #n ")" ::: "memory")
; #define BAR8 __builtin_amdgcn_s_barrier()
; #define SCHED8 __builtin_amdgcn_sched_barrier(0)
;     ...
;     BAR8; WAIT_L8(0); MMA8(1, 0, At, B0); BAR8; SCHED8;
;     STAGE8(SB8(0, 1), Bt, K, bcol + 128, tt + 2);
;     WAIT_V8(6); BAR8; MMA8(1, 1, At, B1); BAR8;
;     LDB8(B0, 1, 0); SCHED8; LDA8(At, 1, 0); STAGE8(SA8(0, 1), A, lda, brow + 128, tt + 2);
;     WAIT_L8(8); BAR8; WAIT_L8(0); MMA8(0, 0, At, B0); BAR8; SCHED8;
;     LDB8(B1, 1, 1); STAGE8(SB8(1, 0), Bt, K, bcol, tt + 3);
;     BAR8; WAIT_L8(0); MMA8(0, 1, At, B1); BAR8;
;     LDA8(At, 1, 1); STAGE8(SA8(1, 0), A, lda, brow, tt + 3);
;     BAR8; WAIT_L8(0); MMA8(1, 0, At, B0); BAR8; SCHED8;
;     STAGE8(SB8(1, 1), Bt, K, bcol + 128, tt + 3);
;     WAIT_V8(6); BAR8; MMA8(1, 1, At, B1); BAR8;
	s_waitcnt lgkmcnt(0)
	s_setprio 1
	s_waitcnt lgkmcnt(0)
	v_mfma_f32_16x16x32_f16 v[128:131], v[190:193], v[174:177], v[128:131]
	v_mfma_f32_16x16x32_f16 v[124:127], v[190:193], v[182:185], v[124:127]
	v_mfma_f32_16x16x32_f16 v[120:123], v[198:201], v[174:177], v[120:123]
	v_mfma_f32_16x16x32_f16 v[116:119], v[198:201], v[182:185], v[116:119]
	v_mfma_f32_16x16x32_f16 v[112:115], v[206:209], v[174:177], v[112:115]
	v_mfma_f32_16x16x32_f16 v[108:111], v[206:209], v[182:185], v[108:111]
	v_mfma_f32_16x16x32_f16 v[104:107], v[214:217], v[174:177], v[104:107]
	v_mfma_f32_16x16x32_f16 v[100:103], v[214:217], v[182:185], v[100:103]
	v_mfma_f32_16x16x32_f16 v[128:131], v[194:197], v[178:181], v[128:131]
	v_mfma_f32_16x16x32_f16 v[124:127], v[194:197], v[186:189], v[124:127]
	v_mfma_f32_16x16x32_f16 v[120:123], v[202:205], v[178:181], v[120:123]
	v_mfma_f32_16x16x32_f16 v[116:119], v[202:205], v[186:189], v[116:119]
	v_mfma_f32_16x16x32_f16 v[112:115], v[210:213], v[178:181], v[112:115]
	v_mfma_f32_16x16x32_f16 v[108:111], v[210:213], v[186:189], v[108:111]
	v_mfma_f32_16x16x32_f16 v[104:107], v[218:221], v[178:181], v[104:107]
	v_mfma_f32_16x16x32_f16 v[100:103], v[218:221], v[186:189], v[100:103]
	s_setprio 0
	s_barrier
	v_readfirstlane_b32 s14, v164
	v_lshl_add_u64 v[250:251], v[246:247], 0, s[42:43]
	s_mov_b32 m0, s14
	v_readfirstlane_b32 s14, v165
	ds_read_b128 v[226:229], v162
	ds_read_b128 v[230:233], v162 offset:1024
	ds_read_b128 v[238:241], v162 offset:2048
	ds_read_b128 v[242:245], v162 offset:3072
	global_load_lds_dwordx4 v[250:251], off
	v_lshl_add_u64 v[250:251], v[248:249], 0, s[42:43]
	s_mov_b32 m0, s14
	s_nop 0
	global_load_lds_dwordx4 v[250:251], off
	s_barrier
	s_waitcnt lgkmcnt(0)
	s_setprio 1
	s_waitcnt lgkmcnt(0)
	v_mfma_f32_16x16x32_f16 v[96:99], v[190:193], v[226:229], v[96:99]
	v_mfma_f32_16x16x32_f16 v[92:95], v[190:193], v[238:241], v[92:95]
	v_mfma_f32_16x16x32_f16 v[88:91], v[198:201], v[226:229], v[88:91]
	v_mfma_f32_16x16x32_f16 v[84:87], v[198:201], v[238:241], v[84:87]
	v_mfma_f32_16x16x32_f16 v[80:83], v[206:209], v[226:229], v[80:83]
	v_mfma_f32_16x16x32_f16 v[76:79], v[206:209], v[238:241], v[76:79]
	v_mfma_f32_16x16x32_f16 v[72:75], v[214:217], v[226:229], v[72:75]
	v_mfma_f32_16x16x32_f16 v[68:71], v[214:217], v[238:241], v[68:71]
	v_mfma_f32_16x16x32_f16 v[96:99], v[194:197], v[230:233], v[96:99]
	v_mfma_f32_16x16x32_f16 v[92:95], v[194:197], v[242:245], v[92:95]
	v_mfma_f32_16x16x32_f16 v[88:91], v[202:205], v[230:233], v[88:91]
	v_mfma_f32_16x16x32_f16 v[84:87], v[202:205], v[242:245], v[84:87]
	v_mfma_f32_16x16x32_f16 v[80:83], v[210:213], v[230:233], v[80:83]
	v_mfma_f32_16x16x32_f16 v[76:79], v[210:213], v[242:245], v[76:79]
	v_mfma_f32_16x16x32_f16 v[72:75], v[218:221], v[230:233], v[72:75]
	v_mfma_f32_16x16x32_f16 v[68:71], v[218:221], v[242:245], v[68:71]
	s_setprio 0
	v_readfirstlane_b32 s14, v166
	v_lshl_add_u64 v[222:223], v[222:223], 0, s[22:23]
	s_mov_b32 m0, s14
	v_readfirstlane_b32 s14, v167
	s_barrier
	ds_read_b128 v[190:193], v161 offset:49152
	ds_read_b128 v[194:197], v161 offset:50176
	ds_read_b128 v[198:201], v160 offset:49152
	ds_read_b128 v[202:205], v160 offset:50176
	ds_read_b128 v[206:209], v159 offset:49152
	ds_read_b128 v[210:213], v159 offset:50176
	ds_read_b128 v[214:217], v158 offset:49152
	ds_read_b128 v[218:221], v158 offset:50176
	global_load_lds_dwordx4 v[222:223], off
	v_lshl_add_u64 v[222:223], v[236:237], 0, s[22:23]
	s_mov_b32 m0, s14
	s_nop 0
	global_load_lds_dwordx4 v[222:223], off
	s_barrier
	s_waitcnt lgkmcnt(0)
	s_setprio 1
	s_waitcnt lgkmcnt(0)
	v_mfma_f32_16x16x32_f16 v[64:67], v[190:193], v[174:177], v[64:67]
	v_mfma_f32_16x16x32_f16 v[60:63], v[190:193], v[182:185], v[60:63]
	v_mfma_f32_16x16x32_f16 v[56:59], v[198:201], v[174:177], v[56:59]
	v_mfma_f32_16x16x32_f16 v[52:55], v[198:201], v[182:185], v[52:55]
	v_mfma_f32_16x16x32_f16 v[48:51], v[206:209], v[174:177], v[48:51]
	v_mfma_f32_16x16x32_f16 v[44:47], v[206:209], v[182:185], v[44:47]
	v_mfma_f32_16x16x32_f16 v[40:43], v[214:217], v[174:177], v[40:43]
	v_mfma_f32_16x16x32_f16 v[36:39], v[214:217], v[182:185], v[36:39]
	v_mfma_f32_16x16x32_f16 v[64:67], v[194:197], v[178:181], v[64:67]
	v_mfma_f32_16x16x32_f16 v[60:63], v[194:197], v[186:189], v[60:63]
	v_mfma_f32_16x16x32_f16 v[56:59], v[202:205], v[178:181], v[56:59]
	v_mfma_f32_16x16x32_f16 v[52:55], v[202:205], v[186:189], v[52:55]
	v_mfma_f32_16x16x32_f16 v[48:51], v[210:213], v[178:181], v[48:51]
	v_mfma_f32_16x16x32_f16 v[44:47], v[210:213], v[186:189], v[44:47]
	v_mfma_f32_16x16x32_f16 v[40:43], v[218:221], v[178:181], v[40:43]
	v_mfma_f32_16x16x32_f16 v[36:39], v[218:221], v[186:189], v[36:39]
	s_setprio 0
	s_barrier
	v_readfirstlane_b32 s14, v168
	v_lshl_add_u64 v[174:175], v[246:247], 0, s[44:45]
	s_mov_b32 m0, s14
	v_readfirstlane_b32 s14, v170
	global_load_lds_dwordx4 v[174:175], off
	v_lshl_add_u64 v[174:175], v[248:249], 0, s[44:45]
	s_mov_b32 m0, s14
	s_nop 0
	global_load_lds_dwordx4 v[174:175], off
	v_add_u32_e32 v176, 0xc000, v150
	v_lshl_add_u64 v[174:175], v[138:139], 0, s[12:13]
	v_add_u32_e32 v177, 0xe000, v150
	v_readfirstlane_b32 s14, v176
	v_lshl_add_u64 v[174:175], v[174:175], 0, s[100:101]
	s_mov_b32 m0, s14
	v_readfirstlane_b32 s14, v177
	global_load_lds_dwordx4 v[174:175], off
	v_lshl_add_u64 v[174:175], v[236:237], 0, s[100:101]
	s_mov_b32 m0, s14
	s_nop 0
	global_load_lds_dwordx4 v[174:175], off
	s_waitcnt vmcnt(8)
	s_barrier
; #define LDA8(dst, b, h) _Pragma("unroll") for (int m = 0; m < 4; ++m) _Pragma("unroll") for (int k = 0; k < 2; ++k) \
;     dst[m][k] = *(const bf16x8*)((const char*)SA8(b, h) + lds_byte8(wr * 64 + m * 16 + fr, k * 32 + fq * 8))
; #define LDB8(dst, b, h) _Pragma("unroll") for (int n = 0; n < 2; ++n) _Pragma("unroll") for (int k = 0; k < 2; ++k) \
;     dst[n][k] = *(const bf16x8*)((const char*)SB8(b, h) + lds_byte8(wc * 32 + n * 16 + fr, k * 32 + fq * 8))
; #define WAIT_V8(n) asm volatile("s_waitcnt vmcnt(" #n ")" ::: "memory")
; #define WAIT_L8(n) asm volatile("s_waitcnt lgkmcnt(" #n ")" ::: "memory")
; #define BAR8 __builtin_amdgcn_s_barrier()
;     ...
;     WAIT_V8(6); BAR8; MMA8(1, 1, At, B1); BAR8;
;   }
;   { LDB8(B0, 0, 0); LDA8(At, 0, 0); STAGE8(SA8(1, 1), A, lda, brow + 128, nt - 1);
;     BAR8; WAIT_L8(0); MMA8(0, 0, At, B0); BAR8;
;     LDB8(B1, 0, 1); BAR8; WAIT_L8(0); MMA8(0, 1, At, B1); BAR8;
;     LDA8(At, 0, 1); WAIT_V8(4); BAR8; WAIT_L8(0); MMA8(1, 0, At, B0); MMA8(1, 1, At, B1); BAR8; }
	s_setprio 1
	v_mfma_f32_16x16x32_f16 v[32:35], v[190:193], v[226:229], v[32:35]
	v_mfma_f32_16x16x32_f16 v[28:31], v[190:193], v[238:241], v[28:31]
	v_mfma_f32_16x16x32_f16 v[24:27], v[198:201], v[226:229], v[24:27]
	v_mfma_f32_16x16x32_f16 v[20:23], v[198:201], v[238:241], v[20:23]
	v_mfma_f32_16x16x32_f16 v[16:19], v[206:209], v[226:229], v[16:19]
	v_mfma_f32_16x16x32_f16 v[12:15], v[206:209], v[238:241], v[12:15]
	v_mfma_f32_16x16x32_f16 v[8:11], v[214:217], v[226:229], v[8:11]
	v_mfma_f32_16x16x32_f16 v[4:7], v[214:217], v[238:241], v[4:7]
	v_mfma_f32_16x16x32_f16 v[32:35], v[194:197], v[230:233], v[32:35]
	v_mfma_f32_16x16x32_f16 v[28:31], v[194:197], v[242:245], v[28:31]
	v_mfma_f32_16x16x32_f16 v[24:27], v[202:205], v[230:233], v[24:27]
	v_mfma_f32_16x16x32_f16 v[20:23], v[202:205], v[242:245], v[20:23]
	v_mfma_f32_16x16x32_f16 v[16:19], v[210:213], v[230:233], v[16:19]
	v_mfma_f32_16x16x32_f16 v[12:15], v[210:213], v[242:245], v[12:15]
	v_mfma_f32_16x16x32_f16 v[8:11], v[218:221], v[230:233], v[8:11]
	v_mfma_f32_16x16x32_f16 v[4:7], v[218:221], v[242:245], v[4:7]
	s_setprio 0
	s_add_i32 s1, s1, 2
	s_add_u32 s12, s12, 0x100
	s_addc_u32 s13, s13, 0
	s_cmp_lt_u32 s1, 12
	s_barrier
	s_cbranch_scc1 .LBB0_1259
	s_add_u32 s8, s8, 0x40780
	s_addc_u32 s9, s9, 0
	v_lshl_add_u64 v[132:133], s[8:9], 0, v[132:133]
	v_lshl_add_u64 v[0:1], v[0:1], 1, v[132:133]
	ds_read_b128 v[138:141], v171
	ds_read_b128 v[142:145], v171 offset:1024
	ds_read_b128 v[150:153], v171 offset:2048
	ds_read_b128 v[154:157], v171 offset:3072
	ds_read_b128 v[164:167], v161
	ds_read_b128 v[174:177], v161 offset:1024
	ds_read_b128 v[178:181], v160
	ds_read_b128 v[182:185], v160 offset:1024
	ds_read_b128 v[186:189], v159
	ds_read_b128 v[190:193], v159 offset:1024
	ds_read_b128 v[194:197], v158
	ds_read_b128 v[198:201], v158 offset:1024
	v_lshl_add_u64 v[0:1], s[8:9], 0, v[136:137]
	v_lshl_add_u64 v[0:1], v[134:135], 1, v[0:1]
	s_nop 0
	s_barrier
	s_waitcnt lgkmcnt(0)
	s_setprio 1
	s_waitcnt lgkmcnt(0)
	v_mfma_f32_16x16x32_f16 v[128:131], v[164:167], v[138:141], v[128:131]
	v_mfma_f32_16x16x32_f16 v[124:127], v[164:167], v[150:153], v[124:127]
	v_mfma_f32_16x16x32_f16 v[120:123], v[178:181], v[138:141], v[120:123]
	v_mfma_f32_16x16x32_f16 v[116:119], v[178:181], v[150:153], v[116:119]
	v_mfma_f32_16x16x32_f16 v[104:107], v[194:197], v[138:141], v[104:107]
	v_mfma_f32_16x16x32_f16 v[100:103], v[194:197], v[150:153], v[100:103]
	v_mfma_f32_16x16x32_f16 v[128:131], v[174:177], v[142:145], v[128:131]
	v_mfma_f32_16x16x32_f16 v[124:127], v[174:177], v[154:157], v[124:127]
	v_mfma_f32_16x16x32_f16 v[120:123], v[182:185], v[142:145], v[120:123]
	v_mfma_f32_16x16x32_f16 v[116:119], v[182:185], v[154:157], v[116:119]
	v_mfma_f32_16x16x32_f16 v[112:115], v[186:189], v[138:141], v[112:115]
	v_mfma_f32_16x16x32_f16 v[108:111], v[186:189], v[150:153], v[108:111]
	v_mfma_f32_16x16x32_f16 v[104:107], v[198:201], v[142:145], v[104:107]
	v_mfma_f32_16x16x32_f16 v[100:103], v[198:201], v[154:157], v[100:103]
	v_mfma_f32_16x16x32_f16 v[132:135], v[190:193], v[142:145], v[112:115]
	v_mfma_f32_16x16x32_f16 v[170:173], v[190:193], v[154:157], v[108:111]
	s_setprio 0
	s_barrier
	s_nop 1
	ds_read_b128 v[108:111], v169
	ds_read_b128 v[112:115], v169 offset:1024
	ds_read_b128 v[202:205], v169 offset:2048
	ds_read_b128 v[206:209], v169 offset:3072
	s_barrier
	s_waitcnt lgkmcnt(0)
	s_setprio 1
	s_waitcnt lgkmcnt(0)
	v_mfma_f32_16x16x32_f16 v[88:91], v[178:181], v[108:111], v[88:91]
	v_mfma_f32_16x16x32_f16 v[84:87], v[178:181], v[202:205], v[84:87]
	v_mfma_f32_16x16x32_f16 v[72:75], v[194:197], v[108:111], v[72:75]
	v_mfma_f32_16x16x32_f16 v[68:71], v[194:197], v[202:205], v[68:71]
	v_mfma_f32_16x16x32_f16 v[96:99], v[164:167], v[108:111], v[96:99]
	v_mfma_f32_16x16x32_f16 v[92:95], v[164:167], v[202:205], v[92:95]
	v_mfma_f32_16x16x32_f16 v[88:91], v[182:185], v[112:115], v[88:91]
	v_mfma_f32_16x16x32_f16 v[84:87], v[182:185], v[206:209], v[84:87]
	v_mfma_f32_16x16x32_f16 v[80:83], v[186:189], v[108:111], v[80:83]
	v_mfma_f32_16x16x32_f16 v[76:79], v[186:189], v[202:205], v[76:79]
	v_mfma_f32_16x16x32_f16 v[72:75], v[198:201], v[112:115], v[72:75]
	v_mfma_f32_16x16x32_f16 v[68:71], v[198:201], v[206:209], v[68:71]
	v_mfma_f32_16x16x32_f16 v[210:213], v[174:177], v[112:115], v[96:99]
	v_mfma_f32_16x16x32_f16 v[164:167], v[174:177], v[206:209], v[92:95]
	v_mfma_f32_16x16x32_f16 v[174:177], v[190:193], v[112:115], v[80:83]
	v_mfma_f32_16x16x32_f16 v[178:181], v[190:193], v[206:209], v[76:79]
	s_setprio 0
	s_barrier
	s_nop 0
	ds_read_b128 v[76:79], v161 offset:16384
	ds_read_b128 v[80:83], v161 offset:17408
	ds_read_b128 v[92:95], v160 offset:16384
	ds_read_b128 v[96:99], v160 offset:17408
	ds_read_b128 v[182:185], v159 offset:16384
	ds_read_b128 v[186:189], v159 offset:17408
	ds_read_b128 v[190:193], v158 offset:16384
	ds_read_b128 v[194:197], v158 offset:17408
	s_waitcnt vmcnt(4)
	s_barrier
; #define LDA8(dst, b, h) _Pragma("unroll") for (int m = 0; m < 4; ++m) _Pragma("unroll") for (int k = 0; k < 2; ++k) \
;     dst[m][k] = *(const bf16x8*)((const char*)SA8(b, h) + lds_byte8(wr * 64 + m * 16 + fr, k * 32 + fq * 8))
; #define LDB8(dst, b, h) _Pragma("unroll") for (int n = 0; n < 2; ++n) _Pragma("unroll") for (int k = 0; k < 2; ++k) \
;     dst[n][k] = *(const bf16x8*)((const char*)SB8(b, h) + lds_byte8(wc * 32 + n * 16 + fr, k * 32 + fq * 8))
; #define WAIT_V8(n) asm volatile("s_waitcnt vmcnt(" #n ")" ::: "memory")
; #define WAIT_L8(n) asm volatile("s_waitcnt lgkmcnt(" #n ")" ::: "memory")
; #define BAR8 __builtin_amdgcn_s_barrier()
;     ...
;     LDA8(At, 0, 1); WAIT_V8(4); BAR8; WAIT_L8(0); MMA8(1, 0, At, B0); MMA8(1, 1, At, B1); BAR8; }
;   { LDB8(B0, 1, 0); LDA8(At, 1, 0); WAIT_V8(2); BAR8; WAIT_L8(0); MMA8(0, 0, At, B0); BAR8;
;     LDB8(B1, 1, 1); WAIT_V8(0); BAR8; WAIT_L8(0); MMA8(0, 1, At, B1); BAR8;
;     LDA8(At, 1, 1); BAR8; WAIT_L8(0); MMA8(1, 0, At, B0); MMA8(1, 1, At, B1); BAR8; }
	s_waitcnt lgkmcnt(0)
	s_setprio 1
	s_waitcnt lgkmcnt(0)
	v_mfma_f32_16x16x32_f16 v[64:67], v[76:79], v[138:141], v[64:67]
	v_mfma_f32_16x16x32_f16 v[60:63], v[76:79], v[150:153], v[60:63]
	v_mfma_f32_16x16x32_f16 v[56:59], v[92:95], v[138:141], v[56:59]
	v_mfma_f32_16x16x32_f16 v[52:55], v[92:95], v[150:153], v[52:55]
	v_mfma_f32_16x16x32_f16 v[40:43], v[190:193], v[138:141], v[40:43]
	v_mfma_f32_16x16x32_f16 v[36:39], v[190:193], v[150:153], v[36:39]
	v_mfma_f32_16x16x32_f16 v[64:67], v[80:83], v[142:145], v[64:67]
	v_mfma_f32_16x16x32_f16 v[60:63], v[80:83], v[154:157], v[60:63]
	v_mfma_f32_16x16x32_f16 v[56:59], v[96:99], v[142:145], v[56:59]
	v_mfma_f32_16x16x32_f16 v[52:55], v[96:99], v[154:157], v[52:55]
	v_mfma_f32_16x16x32_f16 v[48:51], v[182:185], v[138:141], v[48:51]
	v_mfma_f32_16x16x32_f16 v[44:47], v[182:185], v[150:153], v[44:47]
	v_mfma_f32_16x16x32_f16 v[40:43], v[194:197], v[142:145], v[40:43]
	v_mfma_f32_16x16x32_f16 v[36:39], v[194:197], v[154:157], v[36:39]
	v_mfma_f32_16x16x32_f16 v[198:201], v[186:189], v[142:145], v[48:51]
	v_mfma_f32_16x16x32_f16 v[214:217], v[186:189], v[154:157], v[44:47]
	s_setprio 0
	s_setprio 1
	v_mfma_f32_16x16x32_f16 v[24:27], v[92:95], v[108:111], v[24:27]
	v_mfma_f32_16x16x32_f16 v[20:23], v[92:95], v[202:205], v[20:23]
	v_mfma_f32_16x16x32_f16 v[8:11], v[190:193], v[108:111], v[8:11]
	v_mfma_f32_16x16x32_f16 v[4:7], v[190:193], v[202:205], v[4:7]
	v_mfma_f32_16x16x32_f16 v[32:35], v[76:79], v[108:111], v[32:35]
	v_mfma_f32_16x16x32_f16 v[28:31], v[76:79], v[202:205], v[28:31]
	v_mfma_f32_16x16x32_f16 v[24:27], v[96:99], v[112:115], v[24:27]
	v_mfma_f32_16x16x32_f16 v[20:23], v[96:99], v[206:209], v[20:23]
	v_mfma_f32_16x16x32_f16 v[16:19], v[182:185], v[108:111], v[16:19]
	v_mfma_f32_16x16x32_f16 v[12:15], v[182:185], v[202:205], v[12:15]
	v_mfma_f32_16x16x32_f16 v[8:11], v[194:197], v[112:115], v[8:11]
	v_mfma_f32_16x16x32_f16 v[4:7], v[194:197], v[206:209], v[4:7]
	v_mfma_f32_16x16x32_f16 v[136:139], v[80:83], v[112:115], v[32:35]
	v_mfma_f32_16x16x32_f16 v[140:143], v[80:83], v[206:209], v[28:31]
	v_mfma_f32_16x16x32_f16 v[150:153], v[186:189], v[112:115], v[16:19]
	v_mfma_f32_16x16x32_f16 v[154:157], v[186:189], v[206:209], v[12:15]
	s_setprio 0
	s_barrier
	s_nop 0
	ds_read_b128 v[12:15], v163
	ds_read_b128 v[16:19], v163 offset:1024
	ds_read_b128 v[182:185], v163 offset:2048
	ds_read_b128 v[186:189], v163 offset:3072
	ds_read_b128 v[28:31], v161 offset:32768
	ds_read_b128 v[32:35], v161 offset:33792
	ds_read_b128 v[44:47], v160 offset:32768
	ds_read_b128 v[48:51], v160 offset:33792
	ds_read_b128 v[190:193], v159 offset:32768
	ds_read_b128 v[194:197], v159 offset:33792
	ds_read_b128 v[202:205], v158 offset:32768
	ds_read_b128 v[206:209], v158 offset:33792
	s_waitcnt vmcnt(2)
	s_barrier
	s_waitcnt lgkmcnt(0)
	s_setprio 1
	s_waitcnt lgkmcnt(0)
	v_mfma_f32_16x16x32_f16 v[76:79], v[28:31], v[12:15], v[128:131]
	v_mfma_f32_16x16x32_f16 v[128:131], v[32:35], v[16:19], v[76:79]
	v_mfma_f32_16x16x32_f16 v[76:79], v[28:31], v[182:185], v[124:127]
	v_mfma_f32_16x16x32_f16 v[124:127], v[32:35], v[186:189], v[76:79]
	v_mfma_f32_16x16x32_f16 v[76:79], v[44:47], v[12:15], v[120:123]
	v_mfma_f32_16x16x32_f16 v[112:115], v[48:51], v[16:19], v[76:79]
	v_mfma_f32_16x16x32_f16 v[76:79], v[44:47], v[182:185], v[116:119]
	v_mfma_f32_16x16x32_f16 v[108:111], v[48:51], v[186:189], v[76:79]
	v_mfma_f32_16x16x32_f16 v[76:79], v[190:193], v[12:15], v[132:135]
	v_mfma_f32_16x16x32_f16 v[96:99], v[194:197], v[16:19], v[76:79]
	v_mfma_f32_16x16x32_f16 v[76:79], v[190:193], v[182:185], v[170:173]
	v_mfma_f32_16x16x32_f16 v[92:95], v[194:197], v[186:189], v[76:79]
	v_mfma_f32_16x16x32_f16 v[76:79], v[202:205], v[12:15], v[104:107]
	v_mfma_f32_16x16x32_f16 v[80:83], v[206:209], v[16:19], v[76:79]
	v_mfma_f32_16x16x32_f16 v[76:79], v[202:205], v[182:185], v[100:103]
	v_mfma_f32_16x16x32_f16 v[76:79], v[206:209], v[186:189], v[76:79]
	s_setprio 0
	s_barrier
; #define LDA8(dst, b, h) _Pragma("unroll") for (int m = 0; m < 4; ++m) _Pragma("unroll") for (int k = 0; k < 2; ++k) \
;     dst[m][k] = *(const bf16x8*)((const char*)SA8(b, h) + lds_byte8(wr * 64 + m * 16 + fr, k * 32 + fq * 8))
; #define LDB8(dst, b, h) _Pragma("unroll") for (int n = 0; n < 2; ++n) _Pragma("unroll") for (int k = 0; k < 2; ++k) \
;     dst[n][k] = *(const bf16x8*)((const char*)SB8(b, h) + lds_byte8(wc * 32 + n * 16 + fr, k * 32 + fq * 8))
; #define WAIT_V8(n) asm volatile("s_waitcnt vmcnt(" #n ")" ::: "memory")
; #define WAIT_L8(n) asm volatile("s_waitcnt lgkmcnt(" #n ")" ::: "memory")
; #define BAR8 __builtin_amdgcn_s_barrier()
;     ...
;   { LDB8(B0, 1, 0); LDA8(At, 1, 0); WAIT_V8(2); BAR8; WAIT_L8(0); MMA8(0, 0, At, B0); BAR8;
;     LDB8(B1, 1, 1); WAIT_V8(0); BAR8; WAIT_L8(0); MMA8(0, 1, At, B1); BAR8;
;     LDA8(At, 1, 1); BAR8; WAIT_L8(0); MMA8(1, 0, At, B0); MMA8(1, 1, At, B1); BAR8; }
;   if (wr == 0) BAR8;
;   __syncthreads();
;     ...
;   if (t < 256) {
	ds_read_b128 v[132:135], v162
	ds_read_b128 v[168:171], v162 offset:1024
	ds_read_b128 v[218:221], v162 offset:2048
	ds_read_b128 v[226:229], v162 offset:3072
	s_waitcnt vmcnt(0)
	s_barrier
	s_waitcnt lgkmcnt(0)
	s_setprio 1
	s_waitcnt lgkmcnt(0)
	v_mfma_f32_16x16x32_f16 v[100:103], v[28:31], v[132:135], v[210:213]
	v_mfma_f32_16x16x32_f16 v[28:31], v[28:31], v[218:221], v[164:167]
	v_mfma_f32_16x16x32_f16 v[116:119], v[32:35], v[226:229], v[28:31]
	v_mfma_f32_16x16x32_f16 v[28:31], v[44:47], v[132:135], v[88:91]
	v_mfma_f32_16x16x32_f16 v[104:107], v[48:51], v[168:171], v[28:31]
	v_mfma_f32_16x16x32_f16 v[28:31], v[44:47], v[218:221], v[84:87]
	v_mfma_f32_16x16x32_f16 v[120:123], v[32:35], v[168:171], v[100:103]
	v_mfma_f32_16x16x32_f16 v[100:103], v[48:51], v[226:229], v[28:31]
	v_mfma_f32_16x16x32_f16 v[28:31], v[190:193], v[132:135], v[174:177]
	v_mfma_f32_16x16x32_f16 v[88:91], v[194:197], v[168:171], v[28:31]
	v_mfma_f32_16x16x32_f16 v[28:31], v[190:193], v[218:221], v[178:181]
	v_mfma_f32_16x16x32_f16 v[84:87], v[194:197], v[226:229], v[28:31]
	v_mfma_f32_16x16x32_f16 v[28:31], v[202:205], v[132:135], v[72:75]
	v_mfma_f32_16x16x32_f16 v[72:75], v[206:209], v[168:171], v[28:31]
	v_mfma_f32_16x16x32_f16 v[28:31], v[202:205], v[218:221], v[68:71]
	v_mfma_f32_16x16x32_f16 v[68:71], v[206:209], v[226:229], v[28:31]
	s_setprio 0
	s_barrier
	ds_read_b128 v[162:165], v161 offset:49152
	ds_read_b128 v[172:175], v161 offset:50176
	ds_read_b128 v[176:179], v160 offset:49152
	ds_read_b128 v[190:193], v160 offset:50176
	ds_read_b128 v[194:197], v159 offset:49152
	ds_read_b128 v[202:205], v159 offset:50176
	ds_read_b128 v[206:209], v158 offset:49152
	ds_read_b128 v[158:161], v158 offset:50176
	s_barrier
	s_waitcnt lgkmcnt(0)
	s_setprio 1
	s_waitcnt lgkmcnt(0)
	v_mfma_f32_16x16x32_f16 v[28:31], v[162:165], v[12:15], v[64:67]
	v_mfma_f32_16x16x32_f16 v[64:67], v[172:175], v[16:19], v[28:31]
	v_mfma_f32_16x16x32_f16 v[28:31], v[162:165], v[182:185], v[60:63]
	v_mfma_f32_16x16x32_f16 v[60:63], v[172:175], v[186:189], v[28:31]
	v_mfma_f32_16x16x32_f16 v[28:31], v[176:179], v[12:15], v[56:59]
	v_mfma_f32_16x16x32_f16 v[48:51], v[190:193], v[16:19], v[28:31]
	v_mfma_f32_16x16x32_f16 v[28:31], v[176:179], v[182:185], v[52:55]
	v_mfma_f32_16x16x32_f16 v[44:47], v[190:193], v[186:189], v[28:31]
	v_mfma_f32_16x16x32_f16 v[28:31], v[194:197], v[12:15], v[198:201]
	v_mfma_f32_16x16x32_f16 v[12:15], v[206:209], v[12:15], v[40:43]
	v_mfma_f32_16x16x32_f16 v[32:35], v[202:205], v[16:19], v[28:31]
	v_mfma_f32_16x16x32_f16 v[28:31], v[194:197], v[182:185], v[214:217]
	v_mfma_f32_16x16x32_f16 v[16:19], v[158:161], v[16:19], v[12:15]
	v_mfma_f32_16x16x32_f16 v[12:15], v[206:209], v[182:185], v[36:39]
	v_mfma_f32_16x16x32_f16 v[28:31], v[202:205], v[186:189], v[28:31]
	v_mfma_f32_16x16x32_f16 v[12:15], v[158:161], v[186:189], v[12:15]
	s_setprio 0
	s_setprio 1
	v_mfma_f32_16x16x32_f16 v[36:39], v[162:165], v[132:135], v[136:139]
	v_mfma_f32_16x16x32_f16 v[56:59], v[172:175], v[168:171], v[36:39]
	v_mfma_f32_16x16x32_f16 v[36:39], v[162:165], v[218:221], v[140:143]
	v_mfma_f32_16x16x32_f16 v[20:23], v[176:179], v[218:221], v[20:23]
	v_mfma_f32_16x16x32_f16 v[52:55], v[172:175], v[226:229], v[36:39]
	v_mfma_f32_16x16x32_f16 v[24:27], v[176:179], v[132:135], v[24:27]
	v_mfma_f32_16x16x32_f16 v[36:39], v[190:193], v[226:229], v[20:23]
	v_mfma_f32_16x16x32_f16 v[20:23], v[194:197], v[132:135], v[150:153]
	v_mfma_f32_16x16x32_f16 v[40:43], v[190:193], v[168:171], v[24:27]
	v_mfma_f32_16x16x32_f16 v[24:27], v[202:205], v[168:171], v[20:23]
	v_mfma_f32_16x16x32_f16 v[20:23], v[194:197], v[218:221], v[154:157]
	v_mfma_f32_16x16x32_f16 v[8:11], v[206:209], v[132:135], v[8:11]
	v_mfma_f32_16x16x32_f16 v[4:7], v[206:209], v[218:221], v[4:7]
	v_mfma_f32_16x16x32_f16 v[20:23], v[202:205], v[226:229], v[20:23]
	v_mfma_f32_16x16x32_f16 v[8:11], v[158:161], v[168:171], v[8:11]
	v_mfma_f32_16x16x32_f16 v[4:7], v[158:161], v[226:229], v[4:7]
	s_setprio 0
	s_movk_i32 s1, 0x100
	v_cmp_gt_u32_e32 vcc, s1, v3
	s_barrier
	s_and_saveexec_b64 s[8:9], vcc
	s_cbranch_execz .LBB0_1262
	s_barrier
